# k16 with attention softmax exps issued in bursts of 8 (exp x8, add x8, cvt x4 per group) instead of exp/add alternation, MLA and L0 diff tile blocks
# speedup vs baseline: 1.0079x; 1.0079x over previous
; __device__ __forceinline__ float fadd_s(float a, float b) { float r = a + b; asm("" : "+v"(r)); return r; }
; __device__ __forceinline__ unsigned cvtpk(float lo, float hi) { f32x2_t v = {lo, hi}; bf16x2_t b = __builtin_convertvector(v, bf16x2_t); return __builtin_bit_cast(unsigned, b); }
; #define ATT_LOADV(dst, db_) do { const LAS unsigned char* vr_ = vb + (db_) * 32 * VST; _Pragma("unroll") for (int kk = 0; kk < 4; ++kk) dst[kk] = *(const LAS bf16x8*)(vr_ + kk * 32); } while (0)
; template <int DQK, int DV, int MODE, int QPRE, bool DIFF> ...
;     ...
;                 float ls = 0.f;
; #pragma unroll
;                 for (int r = 0; r < 16; ++r) { s0[r] = __builtin_amdgcn_exp2f(s0[r]); s1[r] = __builtin_amdgcn_exp2f(s1[r]); ls = fadd_s(ls, fadd_s(s0[r], s1[r])); }
;                 l_run += ls;
;     ...
;             bf16x8 pb[4];
; #pragma unroll
;             for (int kk = 0; kk < 4; ++kk) {
;                 u32x4 w;
;                 if (kk < 2) { const int b = kk * 8; w.x = cvtpk(s0[b], s0[b + 1]); w.y = cvtpk(s0[b + 2], s0[b + 3]); w.z = cvtpk(s0[b + 4], s0[b + 5]); w.w = cvtpk(s0[b + 6], s0[b + 7]); }
;                 else        { const int b = (kk - 2) * 8; w.x = cvtpk(s1[b], s1[b + 1]); w.y = cvtpk(s1[b + 2], s1[b + 3]); w.z = cvtpk(s1[b + 4], s1[b + 5]); w.w = cvtpk(s1[b + 6], s1[b + 7]); }
;                 pb[kk] = __builtin_bit_cast(bf16x8, w);
;             }
;             __builtin_amdgcn_sched_barrier(0);
; #pragma unroll
;             for (int dbp = 0; dbp < NDB; dbp += 2) {
; #pragma unroll
;                 for (int kk = 0; kk < 4; ++kk) o[dbp] = __builtin_amdgcn_mfma_f32_32x32x16_bf16(vf[0][kk], pb[kk], o[dbp], 0, 0, 0);
;                 if (DEEP) ATT_LOADV(vf[0], dbp + 1);
; #pragma unroll
;                 for (int kk = 0; kk < 4; ++kk) o[dbp + 1] = __builtin_amdgcn_mfma_f32_32x32x16_bf16(vf[DEEP ? 0 : 1][kk], pb[kk], o[dbp + 1], 0, 0, 0);
;                 if (dbp + 2 < NDB) { ATT_LOADV(vf[0], dbp + 2); ATT_LOADV(vf[1], dbp + 3); }
;             }
.Ldf_back0:
	v_exp_f32_e32 v80, v80
	v_exp_f32_e32 v81, v81
	v_exp_f32_e32 v82, v82
	v_exp_f32_e32 v83, v83
	v_exp_f32_e32 v84, v84
	v_exp_f32_e32 v85, v85
	v_exp_f32_e32 v86, v86
	v_exp_f32_e32 v87, v87
	v_add_f32_e32 v223, v80, v81
	v_add_f32_e32 v223, v223, v82
	v_add_f32_e32 v223, v223, v83
	v_add_f32_e32 v223, v223, v84
	v_add_f32_e32 v223, v223, v85
	v_add_f32_e32 v223, v223, v86
	v_add_f32_e32 v223, v223, v87
	v_cvt_pk_bf16_f32 v80, v80, v81
	v_cvt_pk_bf16_f32 v81, v82, v83
	v_cvt_pk_bf16_f32 v82, v84, v85
	v_cvt_pk_bf16_f32 v83, v86, v87
	v_exp_f32_e32 v88, v88
	v_exp_f32_e32 v89, v89
	v_exp_f32_e32 v90, v90
	v_exp_f32_e32 v91, v91
	v_exp_f32_e32 v92, v92
	v_exp_f32_e32 v93, v93
	v_exp_f32_e32 v94, v94
	v_exp_f32_e32 v95, v95
	v_add_f32_e32 v223, v223, v88
	v_add_f32_e32 v223, v223, v89
	v_add_f32_e32 v223, v223, v90
	v_add_f32_e32 v223, v223, v91
	v_add_f32_e32 v223, v223, v92
	v_add_f32_e32 v223, v223, v93
	v_add_f32_e32 v223, v223, v94
	v_add_f32_e32 v223, v223, v95
	v_cvt_pk_bf16_f32 v84, v88, v89
	v_cvt_pk_bf16_f32 v85, v90, v91
	v_cvt_pk_bf16_f32 v86, v92, v93
	v_cvt_pk_bf16_f32 v87, v94, v95
	v_exp_f32_e32 v96, v96
	v_exp_f32_e32 v97, v97
	v_exp_f32_e32 v98, v98
	v_exp_f32_e32 v99, v99
	v_exp_f32_e32 v100, v100
	v_exp_f32_e32 v101, v101
	v_exp_f32_e32 v102, v102
	v_exp_f32_e32 v103, v103
	v_add_f32_e32 v224, v96, v97
	v_add_f32_e32 v224, v224, v98
	v_add_f32_e32 v224, v224, v99
	v_add_f32_e32 v224, v224, v100
	v_add_f32_e32 v224, v224, v101
	v_add_f32_e32 v224, v224, v102
	v_add_f32_e32 v224, v224, v103
	v_cvt_pk_bf16_f32 v88, v96, v97
	v_cvt_pk_bf16_f32 v89, v98, v99
	v_cvt_pk_bf16_f32 v90, v100, v101
	v_cvt_pk_bf16_f32 v91, v102, v103
	v_exp_f32_e32 v104, v104
	v_exp_f32_e32 v105, v105
	v_exp_f32_e32 v106, v106
	v_exp_f32_e32 v107, v107
	v_exp_f32_e32 v108, v108
	v_exp_f32_e32 v109, v109
	v_exp_f32_e32 v110, v110
	v_exp_f32_e32 v111, v111
	v_add_f32_e32 v224, v224, v104
	v_add_f32_e32 v224, v224, v105
	v_add_f32_e32 v224, v224, v106
	v_add_f32_e32 v224, v224, v107
	v_add_f32_e32 v224, v224, v108
	v_add_f32_e32 v224, v224, v109
	v_add_f32_e32 v224, v224, v110
	v_add_f32_e32 v224, v224, v111
	v_cvt_pk_bf16_f32 v92, v104, v105
	v_cvt_pk_bf16_f32 v93, v106, v107
	v_cvt_pk_bf16_f32 v94, v108, v109
	v_cvt_pk_bf16_f32 v95, v110, v111
	v_add_f32_e32 v223, v223, v224
	v_add_f32_e32 v203, v203, v223
	s_waitcnt lgkmcnt(7)
	v_mfma_f32_32x32x16_bf16 v[48:63], v[240:243], v[80:83], v[48:63]
	ds_read_b128 v[168:171], v221 offset:9280
	s_waitcnt lgkmcnt(7)
	v_mfma_f32_32x32x16_bf16 v[32:47], v[244:247], v[80:83], v[32:47]
	ds_read_b128 v[172:175], v221 offset:13888
	s_waitcnt lgkmcnt(7)
	v_mfma_f32_32x32x16_bf16 v[0:15], v[248:251], v[80:83], v[0:15]
	ds_read_b128 v[176:179], v221 offset:18496
	s_waitcnt lgkmcnt(7)
	v_mfma_f32_32x32x16_bf16 v[16:31], v[148:151], v[80:83], v[16:31]
	ds_read_b128 v[240:243], v221 offset:23104
	s_waitcnt lgkmcnt(7)
	v_mfma_f32_32x32x16_bf16 v[48:63], v[152:155], v[84:87], v[48:63]
	ds_read_b128 v[244:247], v221 offset:9312
	s_waitcnt lgkmcnt(7)
	v_mfma_f32_32x32x16_bf16 v[32:47], v[156:159], v[84:87], v[32:47]
	ds_read_b128 v[248:251], v221 offset:13920
	s_waitcnt lgkmcnt(7)
	v_mfma_f32_32x32x16_bf16 v[0:15], v[160:163], v[84:87], v[0:15]
	ds_read_b128 v[148:151], v221 offset:18528
	s_waitcnt lgkmcnt(7)
	v_mfma_f32_32x32x16_bf16 v[16:31], v[164:167], v[84:87], v[16:31]
	ds_read_b128 v[152:155], v221 offset:23136
	s_waitcnt lgkmcnt(7)
	v_mfma_f32_32x32x16_bf16 v[48:63], v[168:171], v[88:91], v[48:63]
	s_waitcnt lgkmcnt(6)
	v_mfma_f32_32x32x16_bf16 v[32:47], v[172:175], v[88:91], v[32:47]
	s_waitcnt lgkmcnt(5)
	v_mfma_f32_32x32x16_bf16 v[0:15], v[176:179], v[88:91], v[0:15]
	s_waitcnt lgkmcnt(4)
	v_mfma_f32_32x32x16_bf16 v[16:31], v[240:243], v[88:91], v[16:31]
	s_waitcnt lgkmcnt(3)
	v_mfma_f32_32x32x16_bf16 v[48:63], v[244:247], v[92:95], v[48:63]
	s_waitcnt lgkmcnt(2)
	v_mfma_f32_32x32x16_bf16 v[32:47], v[248:251], v[92:95], v[32:47]
	s_waitcnt lgkmcnt(1)
	v_mfma_f32_32x32x16_bf16 v[0:15], v[148:151], v[92:95], v[0:15]
	s_waitcnt lgkmcnt(0)
	v_mfma_f32_32x32x16_bf16 v[16:31], v[152:155], v[92:95], v[16:31]
	s_cmp_ge_u32 s6, s31
	s_cbranch_scc1 .LBB0_570

; template <int DQK, int DV, int MODE, int QPRE, bool DIFF> ...
;     ...
;                 float ls = 0.f;
; #pragma unroll
;                 for (int r = 0; r < 16; ++r) { s0[r] = __builtin_amdgcn_exp2f(s0[r]); s1[r] = __builtin_amdgcn_exp2f(s1[r]); ls = fadd_s(ls, fadd_s(s0[r], s1[r])); }
;                 l_run += ls;
;             } else {
;                 const bool diag = (t == my_last);
;                 const int qrel = q0 + wid * 32 + l32 - t * 64;
;                 float kp[32], gprod[8];
; #pragma unroll
;                 for (int k = 0; k < 8; ++k) {
; #pragma unroll
;                     for (int e = 0; e < 4; ++e) {
;                         const int r = (k & 3) * 4 + e;
;                         const float z2 = __builtin_amdgcn_fmed3f((k < 4) ? s0[r] : s1[r], -126.0f, 126.0f);
;                         const float E = __builtin_amdgcn_exp2f(z2);
;                         const float keep = __builtin_amdgcn_rcpf(fadd_s(E, 1.0f)), beta = fmul_s(E, keep);
;                         kp[k * 4 + e] = keep;
;                         if (k < 4) s0[r] = beta; else s1[r] = beta;
;                     }
;                 }
;                 if (diag) {
;                     asm volatile("" ::: "memory");
; #pragma unroll
;                     for (int k = 0; k < 8; ++k)
; #pragma unroll
;                         for (int e = 0; e < 4; ++e) { const int r = (k & 3) * 4 + e; const int kl = (k >> 2) * 32 + e + 8 * (k & 3) + 4 * hi; const bool valid = kl < qrel;
;                             kp[k * 4 + e] = valid ? kp[k * 4 + e] : 1.0f; if (k < 4) s0[r] = valid ? s0[r] : 0.f; else s1[r] = valid ? s1[r] : 0.f; }
;                 }
; #pragma unroll
;                 for (int k = 0; k < 8; ++k) gprod[k] = fmul_s(fmul_s(kp[k * 4], kp[k * 4 + 1]), fmul_s(kp[k * 4 + 2], kp[k * 4 + 3]));
;                 float base[8]; float suf = 1.0f;
; #pragma unroll
;                 for (int k = 7; k >= 0; --k) { float glo, ghi; swap32(gprod[k], glo, ghi); base[k] = fmul_s(fmul_s(Rp, suf), (hi == 0 ? ghi : 1.0f)); suf = fmul_s(suf, fmul_s(glo, ghi)); }
;                 Rp *= suf;
;                 { const bool nd = __all(Rp == 0.0f); if (nd && !sb_done && lane == 0) __hip_atomic_fetch_add(sbcnt, 1u, __ATOMIC_RELAXED, __HIP_MEMORY_SCOPE_WORKGROUP); sb_done = nd; }
; #pragma unroll
;                 for (int k = 0; k < 8; ++k) {
.Lmla_back0a:
	v_exp_f32_e32 v48, v48
	v_exp_f32_e32 v49, v49
	v_exp_f32_e32 v50, v50
	v_exp_f32_e32 v51, v51
	v_exp_f32_e32 v52, v52
	v_exp_f32_e32 v53, v53
	v_exp_f32_e32 v54, v54
	v_exp_f32_e32 v55, v55
	v_add_f32_e32 v252, v48, v49
	v_add_f32_e32 v252, v252, v50
	v_add_f32_e32 v252, v252, v51
	v_add_f32_e32 v252, v252, v52
	v_add_f32_e32 v252, v252, v53
	v_add_f32_e32 v252, v252, v54
	v_add_f32_e32 v252, v252, v55
	v_cvt_pk_bf16_f32 v48, v48, v49
	v_cvt_pk_bf16_f32 v49, v50, v51
	v_cvt_pk_bf16_f32 v50, v52, v53
	v_cvt_pk_bf16_f32 v51, v54, v55
	v_exp_f32_e32 v56, v56
	v_exp_f32_e32 v57, v57
	v_exp_f32_e32 v58, v58
	v_exp_f32_e32 v59, v59
	v_exp_f32_e32 v60, v60
	v_exp_f32_e32 v61, v61
	v_exp_f32_e32 v62, v62
	v_exp_f32_e32 v63, v63
	v_add_f32_e32 v252, v252, v56
	v_add_f32_e32 v252, v252, v57
	v_add_f32_e32 v252, v252, v58
	v_add_f32_e32 v252, v252, v59
	v_add_f32_e32 v252, v252, v60
	v_add_f32_e32 v252, v252, v61
	v_add_f32_e32 v252, v252, v62
	v_add_f32_e32 v252, v252, v63
	v_cvt_pk_bf16_f32 v52, v56, v57
	v_cvt_pk_bf16_f32 v53, v58, v59
	v_cvt_pk_bf16_f32 v54, v60, v61
	v_cvt_pk_bf16_f32 v55, v62, v63
	v_exp_f32_e32 v64, v64
	v_exp_f32_e32 v65, v65
	v_exp_f32_e32 v66, v66
	v_exp_f32_e32 v67, v67
	v_exp_f32_e32 v68, v68
	v_exp_f32_e32 v69, v69
	v_exp_f32_e32 v70, v70
	v_exp_f32_e32 v71, v71
	v_add_f32_e32 v253, v64, v65
	v_add_f32_e32 v253, v253, v66
	v_add_f32_e32 v253, v253, v67
	v_add_f32_e32 v253, v253, v68
	v_add_f32_e32 v253, v253, v69
	v_add_f32_e32 v253, v253, v70
	v_add_f32_e32 v253, v253, v71
	v_cvt_pk_bf16_f32 v56, v64, v65
	v_cvt_pk_bf16_f32 v57, v66, v67
	v_cvt_pk_bf16_f32 v58, v68, v69
	v_cvt_pk_bf16_f32 v59, v70, v71
	v_exp_f32_e32 v72, v72
	v_exp_f32_e32 v73, v73
	v_exp_f32_e32 v74, v74
	v_exp_f32_e32 v75, v75
	v_exp_f32_e32 v76, v76
	v_exp_f32_e32 v77, v77
	v_exp_f32_e32 v78, v78
	v_exp_f32_e32 v79, v79
	v_add_f32_e32 v253, v253, v72
	v_add_f32_e32 v253, v253, v73
	v_add_f32_e32 v253, v253, v74
	v_add_f32_e32 v253, v253, v75
	v_add_f32_e32 v253, v253, v76
	v_add_f32_e32 v253, v253, v77
	v_add_f32_e32 v253, v253, v78
	v_add_f32_e32 v253, v253, v79
	v_cvt_pk_bf16_f32 v60, v72, v73
	v_cvt_pk_bf16_f32 v61, v74, v75
	v_cvt_pk_bf16_f32 v62, v76, v77
	v_cvt_pk_bf16_f32 v63, v78, v79
	v_add_f32_e32 v252, v252, v253
	v_add_f32_e32 v196, v196, v252
	s_waitcnt lgkmcnt(5)
	v_mfma_f32_32x32x16_bf16 v[16:31], v[236:239], v[48:51], v[16:31]
	ds_read_b128 v[160:163], v198 offset:13408
	s_waitcnt lgkmcnt(5)
	v_mfma_f32_32x32x16_bf16 v[0:15], v[240:243], v[48:51], v[0:15]
	ds_read_b128 v[164:167], v198 offset:18016
	s_waitcnt lgkmcnt(5)
	v_mfma_f32_32x32x16_bf16 v[16:31], v[244:247], v[52:55], v[16:31]
	ds_read_b128 v[236:239], v195 offset:22528
	s_waitcnt lgkmcnt(5)
	v_mfma_f32_32x32x16_bf16 v[0:15], v[248:251], v[52:55], v[0:15]
	ds_read_b128 v[240:243], v195 offset:29184
	s_waitcnt lgkmcnt(5)
	v_mfma_f32_32x32x16_bf16 v[16:31], v[152:155], v[56:59], v[16:31]
	ds_read_b128 v[244:247], v195 offset:22560
	s_waitcnt lgkmcnt(5)
	v_mfma_f32_32x32x16_bf16 v[0:15], v[156:159], v[56:59], v[0:15]
	ds_read_b128 v[248:251], v195 offset:29216
	s_waitcnt lgkmcnt(5)
	v_mfma_f32_32x32x16_bf16 v[16:31], v[160:163], v[60:63], v[16:31]
	ds_read_b128 v[152:155], v195 offset:22592
	s_waitcnt lgkmcnt(5)
	v_mfma_f32_32x32x16_bf16 v[0:15], v[164:167], v[60:63], v[0:15]
	ds_read_b128 v[156:159], v195 offset:29248
	s_waitcnt lgkmcnt(5)
	v_mfma_f32_32x32x16_bf16 v[204:219], v[236:239], v[128:131], v[32:47]
	ds_read_b128 v[160:163], v195 offset:22624
	s_waitcnt lgkmcnt(5)
	v_mfma_f32_32x32x16_bf16 v[220:235], v[240:243], v[128:131], v[32:47]
	ds_read_b128 v[164:167], v195 offset:29280
	s_waitcnt lgkmcnt(5)
	v_mfma_f32_32x32x16_bf16 v[204:219], v[244:247], v[132:135], v[204:219]
	ds_read_b128 v[236:239], v195 offset:22656
	s_waitcnt lgkmcnt(5)
	v_mfma_f32_32x32x16_bf16 v[220:235], v[248:251], v[132:135], v[220:235]
	ds_read_b128 v[240:243], v195 offset:29312
	s_waitcnt lgkmcnt(5)
	v_mfma_f32_32x32x16_bf16 v[204:219], v[152:155], v[136:139], v[204:219]
	ds_read_b128 v[244:247], v195 offset:22688
	s_waitcnt lgkmcnt(5)
	v_mfma_f32_32x32x16_bf16 v[220:235], v[156:159], v[136:139], v[220:235]
	ds_read_b128 v[248:251], v195 offset:29344
	s_waitcnt lgkmcnt(5)
	v_mfma_f32_32x32x16_bf16 v[204:219], v[160:163], v[140:143], v[204:219]
	ds_read_b128 v[152:155], v198 offset:35840
	s_waitcnt lgkmcnt(5)
	v_mfma_f32_32x32x16_bf16 v[220:235], v[164:167], v[140:143], v[220:235]
	ds_read_b128 v[156:159], v198 offset:40448
	s_waitcnt lgkmcnt(5)
	v_mfma_f32_32x32x16_bf16 v[204:219], v[236:239], v[144:147], v[204:219]
	ds_read_b128 v[160:163], v198 offset:35872
	s_waitcnt lgkmcnt(5)
	v_mfma_f32_32x32x16_bf16 v[220:235], v[240:243], v[144:147], v[220:235]
	ds_read_b128 v[164:167], v198 offset:40480
	s_waitcnt lgkmcnt(5)
	v_mfma_f32_32x32x16_bf16 v[204:219], v[244:247], v[148:151], v[204:219]
	ds_read_b128 v[236:239], v198 offset:35904
	s_waitcnt lgkmcnt(5)
	v_mfma_f32_32x32x16_bf16 v[220:235], v[248:251], v[148:151], v[220:235]
	ds_read_b128 v[240:243], v198 offset:40512
	s_nop 7
	v_max3_f32 v199, v204, v205, v206
	s_nop 1
	v_max3_f32 v252, v220, v221, v222
	v_max3_f32 v199, v199, v207, v208
	v_max3_f32 v252, v252, v223, v224
	v_max3_f32 v199, v199, v209, v210
	v_max3_f32 v252, v252, v225, v226
	v_max3_f32 v199, v199, v211, v212
	v_max3_f32 v252, v252, v227, v228
	v_max3_f32 v199, v199, v213, v214
	v_max3_f32 v252, v252, v229, v230
	v_max3_f32 v199, v199, v215, v216
	v_max3_f32 v252, v252, v231, v232
	v_max3_f32 v199, v199, v217, v218
	v_max3_f32 v252, v252, v233, v234
	v_max3_f32 v199, v199, v219, v235
	v_max_f32_e32 v199, v199, v252
	v_mov_b32_e32 v252, v199
	s_nop 1
	v_permlane32_swap_b32_e32 v199, v252
	v_max_f32_e32 v199, v199, v252
	v_cmp_lt_f32_e32 vcc, s51, v199
	s_cbranch_vccnz .Lmla_rare0b
; template <int DQK, int DV, int MODE, int QPRE, bool DIFF> ...
;     ...
;                 float ls = 0.f;
; #pragma unroll
;                 for (int r = 0; r < 16; ++r) { s0[r] = __builtin_amdgcn_exp2f(s0[r]); s1[r] = __builtin_amdgcn_exp2f(s1[r]); ls = fadd_s(ls, fadd_s(s0[r], s1[r])); }
;                 l_run += ls;
;             } else {
;                 const bool diag = (t == my_last);
;                 const int qrel = q0 + wid * 32 + l32 - t * 64;
;                 float kp[32], gprod[8];
; #pragma unroll
;                 for (int k = 0; k < 8; ++k) {
; #pragma unroll
;                     for (int e = 0; e < 4; ++e) {
;                         const int r = (k & 3) * 4 + e;
;                         const float z2 = __builtin_amdgcn_fmed3f((k < 4) ? s0[r] : s1[r], -126.0f, 126.0f);
;                         const float E = __builtin_amdgcn_exp2f(z2);
;                         const float keep = __builtin_amdgcn_rcpf(fadd_s(E, 1.0f)), beta = fmul_s(E, keep);
;                         kp[k * 4 + e] = keep;
;                         if (k < 4) s0[r] = beta; else s1[r] = beta;
;                     }
;                 }
;                 if (diag) {
;                     asm volatile("" ::: "memory");
; #pragma unroll
;                     for (int k = 0; k < 8; ++k)
; #pragma unroll
;                         for (int e = 0; e < 4; ++e) { const int r = (k & 3) * 4 + e; const int kl = (k >> 2) * 32 + e + 8 * (k & 3) + 4 * hi; const bool valid = kl < qrel;
;                             kp[k * 4 + e] = valid ? kp[k * 4 + e] : 1.0f; if (k < 4) s0[r] = valid ? s0[r] : 0.f; else s1[r] = valid ? s1[r] : 0.f; }
;                 }
; #pragma unroll
;                 for (int k = 0; k < 8; ++k) gprod[k] = fmul_s(fmul_s(kp[k * 4], kp[k * 4 + 1]), fmul_s(kp[k * 4 + 2], kp[k * 4 + 3]));
;                 float base[8]; float suf = 1.0f;
; #pragma unroll
;                 for (int k = 7; k >= 0; --k) { float glo, ghi; swap32(gprod[k], glo, ghi); base[k] = fmul_s(fmul_s(Rp, suf), (hi == 0 ? ghi : 1.0f)); suf = fmul_s(suf, fmul_s(glo, ghi)); }
;                 Rp *= suf;
;                 { const bool nd = __all(Rp == 0.0f); if (nd && !sb_done && lane == 0) __hip_atomic_fetch_add(sbcnt, 1u, __ATOMIC_RELAXED, __HIP_MEMORY_SCOPE_WORKGROUP); sb_done = nd; }
; #pragma unroll
;                 for (int k = 0; k < 8; ++k) {
.Lmla_back0b:
	v_exp_f32_e32 v204, v204
	v_exp_f32_e32 v205, v205
	v_exp_f32_e32 v206, v206
	v_exp_f32_e32 v207, v207
	v_exp_f32_e32 v208, v208
	v_exp_f32_e32 v209, v209
	v_exp_f32_e32 v210, v210
	v_exp_f32_e32 v211, v211
	v_add_f32_e32 v252, v204, v205
	v_add_f32_e32 v252, v252, v206
	v_add_f32_e32 v252, v252, v207
	v_add_f32_e32 v252, v252, v208
	v_add_f32_e32 v252, v252, v209
	v_add_f32_e32 v252, v252, v210
	v_add_f32_e32 v252, v252, v211
	v_cvt_pk_bf16_f32 v204, v204, v205
	v_cvt_pk_bf16_f32 v205, v206, v207
	v_cvt_pk_bf16_f32 v206, v208, v209
	v_cvt_pk_bf16_f32 v207, v210, v211
	v_exp_f32_e32 v212, v212
	v_exp_f32_e32 v213, v213
	v_exp_f32_e32 v214, v214
	v_exp_f32_e32 v215, v215
	v_exp_f32_e32 v216, v216
	v_exp_f32_e32 v217, v217
	v_exp_f32_e32 v218, v218
	v_exp_f32_e32 v219, v219
	v_add_f32_e32 v252, v252, v212
	v_add_f32_e32 v252, v252, v213
	v_add_f32_e32 v252, v252, v214
	v_add_f32_e32 v252, v252, v215
	v_add_f32_e32 v252, v252, v216
	v_add_f32_e32 v252, v252, v217
	v_add_f32_e32 v252, v252, v218
	v_add_f32_e32 v252, v252, v219
	v_cvt_pk_bf16_f32 v208, v212, v213
	v_cvt_pk_bf16_f32 v209, v214, v215
	v_cvt_pk_bf16_f32 v210, v216, v217
	v_cvt_pk_bf16_f32 v211, v218, v219
	v_exp_f32_e32 v220, v220
	v_exp_f32_e32 v221, v221
	v_exp_f32_e32 v222, v222
	v_exp_f32_e32 v223, v223
	v_exp_f32_e32 v224, v224
	v_exp_f32_e32 v225, v225
	v_exp_f32_e32 v226, v226
	v_exp_f32_e32 v227, v227
	v_add_f32_e32 v253, v220, v221
	v_add_f32_e32 v253, v253, v222
	v_add_f32_e32 v253, v253, v223
	v_add_f32_e32 v253, v253, v224
	v_add_f32_e32 v253, v253, v225
	v_add_f32_e32 v253, v253, v226
	v_add_f32_e32 v253, v253, v227
	v_cvt_pk_bf16_f32 v212, v220, v221
	v_cvt_pk_bf16_f32 v213, v222, v223
	v_cvt_pk_bf16_f32 v214, v224, v225
	v_cvt_pk_bf16_f32 v215, v226, v227
	v_exp_f32_e32 v228, v228
	v_exp_f32_e32 v229, v229
	v_exp_f32_e32 v230, v230
	v_exp_f32_e32 v231, v231
	v_exp_f32_e32 v232, v232
	v_exp_f32_e32 v233, v233
	v_exp_f32_e32 v234, v234
	v_exp_f32_e32 v235, v235
	v_add_f32_e32 v253, v253, v228
	v_add_f32_e32 v253, v253, v229
	v_add_f32_e32 v253, v253, v230
	v_add_f32_e32 v253, v253, v231
	v_add_f32_e32 v253, v253, v232
	v_add_f32_e32 v253, v253, v233
	v_add_f32_e32 v253, v253, v234
	v_add_f32_e32 v253, v253, v235
	v_cvt_pk_bf16_f32 v216, v228, v229
	v_cvt_pk_bf16_f32 v217, v230, v231
	v_cvt_pk_bf16_f32 v218, v232, v233
	v_cvt_pk_bf16_f32 v219, v234, v235
	v_add_f32_e32 v252, v252, v253
	v_add_f32_e32 v196, v196, v252
	s_waitcnt lgkmcnt(5)
	v_mfma_f32_32x32x16_bf16 v[16:31], v[152:155], v[204:207], v[16:31]
	ds_read_b128 v[244:247], v198 offset:35936
	s_waitcnt lgkmcnt(5)
	v_mfma_f32_32x32x16_bf16 v[0:15], v[156:159], v[204:207], v[0:15]
	ds_read_b128 v[248:251], v198 offset:40544
	s_waitcnt lgkmcnt(5)
	v_mfma_f32_32x32x16_bf16 v[16:31], v[160:163], v[208:211], v[16:31]
	s_waitcnt lgkmcnt(4)
	v_mfma_f32_32x32x16_bf16 v[0:15], v[164:167], v[208:211], v[0:15]
	s_waitcnt lgkmcnt(3)
	v_mfma_f32_32x32x16_bf16 v[16:31], v[236:239], v[212:215], v[16:31]
	s_waitcnt lgkmcnt(2)
	v_mfma_f32_32x32x16_bf16 v[0:15], v[240:243], v[212:215], v[0:15]
	s_waitcnt lgkmcnt(1)
	v_mfma_f32_32x32x16_bf16 v[16:31], v[244:247], v[216:219], v[16:31]
	s_waitcnt lgkmcnt(0)
	v_mfma_f32_32x32x16_bf16 v[0:15], v[248:251], v[216:219], v[0:15]
	s_branch .LBB0_1667

; template <int DQK, int DV, int MODE, int QPRE, bool DIFF> ...
;     ...
;                 float ls = 0.f;
; #pragma unroll
;                 for (int r = 0; r < 16; ++r) { s0[r] = __builtin_amdgcn_exp2f(s0[r]); s1[r] = __builtin_amdgcn_exp2f(s1[r]); ls = fadd_s(ls, fadd_s(s0[r], s1[r])); }
;                 l_run += ls;
;             } else {
;                 const bool diag = (t == my_last);
;                 const int qrel = q0 + wid * 32 + l32 - t * 64;
;                 float kp[32], gprod[8];
; #pragma unroll
;                 for (int k = 0; k < 8; ++k) {
; #pragma unroll
;                     for (int e = 0; e < 4; ++e) {
;                         const int r = (k & 3) * 4 + e;
;                         const float z2 = __builtin_amdgcn_fmed3f((k < 4) ? s0[r] : s1[r], -126.0f, 126.0f);
;                         const float E = __builtin_amdgcn_exp2f(z2);
;                         const float keep = __builtin_amdgcn_rcpf(fadd_s(E, 1.0f)), beta = fmul_s(E, keep);
;                         kp[k * 4 + e] = keep;
;                         if (k < 4) s0[r] = beta; else s1[r] = beta;
;                     }
;                 }
;                 if (diag) {
;                     asm volatile("" ::: "memory");
; #pragma unroll
;                     for (int k = 0; k < 8; ++k)
; #pragma unroll
;                         for (int e = 0; e < 4; ++e) { const int r = (k & 3) * 4 + e; const int kl = (k >> 2) * 32 + e + 8 * (k & 3) + 4 * hi; const bool valid = kl < qrel;
;                             kp[k * 4 + e] = valid ? kp[k * 4 + e] : 1.0f; if (k < 4) s0[r] = valid ? s0[r] : 0.f; else s1[r] = valid ? s1[r] : 0.f; }
;                 }
; #pragma unroll
;                 for (int k = 0; k < 8; ++k) gprod[k] = fmul_s(fmul_s(kp[k * 4], kp[k * 4 + 1]), fmul_s(kp[k * 4 + 2], kp[k * 4 + 3]));
;                 float base[8]; float suf = 1.0f;
; #pragma unroll
;                 for (int k = 7; k >= 0; --k) { float glo, ghi; swap32(gprod[k], glo, ghi); base[k] = fmul_s(fmul_s(Rp, suf), (hi == 0 ? ghi : 1.0f)); suf = fmul_s(suf, fmul_s(glo, ghi)); }
;                 Rp *= suf;
;                 { const bool nd = __all(Rp == 0.0f); if (nd && !sb_done && lane == 0) __hip_atomic_fetch_add(sbcnt, 1u, __ATOMIC_RELAXED, __HIP_MEMORY_SCOPE_WORKGROUP); sb_done = nd; }
; #pragma unroll
;                 for (int k = 0; k < 8; ++k) {
.Lmla_back1a:
	v_exp_f32_e32 v48, v48
	v_exp_f32_e32 v49, v49
	v_exp_f32_e32 v50, v50
	v_exp_f32_e32 v51, v51
	v_exp_f32_e32 v52, v52
	v_exp_f32_e32 v53, v53
	v_exp_f32_e32 v54, v54
	v_exp_f32_e32 v55, v55
	v_add_f32_e32 v252, v48, v49
	v_add_f32_e32 v252, v252, v50
	v_add_f32_e32 v252, v252, v51
	v_add_f32_e32 v252, v252, v52
	v_add_f32_e32 v252, v252, v53
	v_add_f32_e32 v252, v252, v54
	v_add_f32_e32 v252, v252, v55
	v_cvt_pk_bf16_f32 v48, v48, v49
	v_cvt_pk_bf16_f32 v49, v50, v51
	v_cvt_pk_bf16_f32 v50, v52, v53
	v_cvt_pk_bf16_f32 v51, v54, v55
	v_exp_f32_e32 v56, v56
	v_exp_f32_e32 v57, v57
	v_exp_f32_e32 v58, v58
	v_exp_f32_e32 v59, v59
	v_exp_f32_e32 v60, v60
	v_exp_f32_e32 v61, v61
	v_exp_f32_e32 v62, v62
	v_exp_f32_e32 v63, v63
	v_add_f32_e32 v252, v252, v56
	v_add_f32_e32 v252, v252, v57
	v_add_f32_e32 v252, v252, v58
	v_add_f32_e32 v252, v252, v59
	v_add_f32_e32 v252, v252, v60
	v_add_f32_e32 v252, v252, v61
	v_add_f32_e32 v252, v252, v62
	v_add_f32_e32 v252, v252, v63
	v_cvt_pk_bf16_f32 v52, v56, v57
	v_cvt_pk_bf16_f32 v53, v58, v59
	v_cvt_pk_bf16_f32 v54, v60, v61
	v_cvt_pk_bf16_f32 v55, v62, v63
	v_exp_f32_e32 v64, v64
	v_exp_f32_e32 v65, v65
	v_exp_f32_e32 v66, v66
	v_exp_f32_e32 v67, v67
	v_exp_f32_e32 v68, v68
	v_exp_f32_e32 v69, v69
	v_exp_f32_e32 v70, v70
	v_exp_f32_e32 v71, v71
	v_add_f32_e32 v253, v64, v65
	v_add_f32_e32 v253, v253, v66
	v_add_f32_e32 v253, v253, v67
	v_add_f32_e32 v253, v253, v68
	v_add_f32_e32 v253, v253, v69
	v_add_f32_e32 v253, v253, v70
	v_add_f32_e32 v253, v253, v71
	v_cvt_pk_bf16_f32 v56, v64, v65
	v_cvt_pk_bf16_f32 v57, v66, v67
	v_cvt_pk_bf16_f32 v58, v68, v69
	v_cvt_pk_bf16_f32 v59, v70, v71
	v_exp_f32_e32 v72, v72
	v_exp_f32_e32 v73, v73
	v_exp_f32_e32 v74, v74
	v_exp_f32_e32 v75, v75
	v_exp_f32_e32 v76, v76
	v_exp_f32_e32 v77, v77
	v_exp_f32_e32 v78, v78
	v_exp_f32_e32 v79, v79
	v_add_f32_e32 v253, v253, v72
	v_add_f32_e32 v253, v253, v73
	v_add_f32_e32 v253, v253, v74
	v_add_f32_e32 v253, v253, v75
	v_add_f32_e32 v253, v253, v76
	v_add_f32_e32 v253, v253, v77
	v_add_f32_e32 v253, v253, v78
	v_add_f32_e32 v253, v253, v79
	v_cvt_pk_bf16_f32 v60, v72, v73
	v_cvt_pk_bf16_f32 v61, v74, v75
	v_cvt_pk_bf16_f32 v62, v76, v77
	v_cvt_pk_bf16_f32 v63, v78, v79
	v_add_f32_e32 v252, v252, v253
	v_add_f32_e32 v196, v196, v252
	s_waitcnt lgkmcnt(5)
	v_mfma_f32_32x32x16_bf16 v[16:31], v[236:239], v[48:51], v[16:31]
	ds_read_b128 v[160:163], v198 offset:58464
	s_waitcnt lgkmcnt(5)
	v_mfma_f32_32x32x16_bf16 v[0:15], v[240:243], v[48:51], v[0:15]
	ds_read_b128 v[164:167], v198 offset:63072
	s_waitcnt lgkmcnt(5)
	v_mfma_f32_32x32x16_bf16 v[16:31], v[244:247], v[52:55], v[16:31]
	ds_read_b128 v[236:239], v194
	s_waitcnt lgkmcnt(5)
	v_mfma_f32_32x32x16_bf16 v[0:15], v[248:251], v[52:55], v[0:15]
	ds_read_b128 v[240:243], v194 offset:6656
	s_waitcnt lgkmcnt(5)
	v_mfma_f32_32x32x16_bf16 v[16:31], v[152:155], v[56:59], v[16:31]
	ds_read_b128 v[244:247], v194 offset:32
	s_waitcnt lgkmcnt(5)
	v_mfma_f32_32x32x16_bf16 v[0:15], v[156:159], v[56:59], v[0:15]
	ds_read_b128 v[248:251], v194 offset:6688
	s_waitcnt lgkmcnt(5)
	v_mfma_f32_32x32x16_bf16 v[16:31], v[160:163], v[60:63], v[16:31]
	ds_read_b128 v[152:155], v194 offset:64
	s_waitcnt lgkmcnt(5)
	v_mfma_f32_32x32x16_bf16 v[0:15], v[164:167], v[60:63], v[0:15]
	ds_read_b128 v[156:159], v194 offset:6720
	s_waitcnt lgkmcnt(5)
	v_mfma_f32_32x32x16_bf16 v[204:219], v[236:239], v[128:131], v[32:47]
	ds_read_b128 v[160:163], v194 offset:96
	s_waitcnt lgkmcnt(5)
	v_mfma_f32_32x32x16_bf16 v[220:235], v[240:243], v[128:131], v[32:47]
	ds_read_b128 v[164:167], v194 offset:6752
	s_waitcnt lgkmcnt(5)
	v_mfma_f32_32x32x16_bf16 v[204:219], v[244:247], v[132:135], v[204:219]
	ds_read_b128 v[236:239], v194 offset:128
	s_waitcnt lgkmcnt(5)
	v_mfma_f32_32x32x16_bf16 v[220:235], v[248:251], v[132:135], v[220:235]
	ds_read_b128 v[240:243], v194 offset:6784
	s_waitcnt lgkmcnt(5)
	v_mfma_f32_32x32x16_bf16 v[204:219], v[152:155], v[136:139], v[204:219]
	ds_read_b128 v[244:247], v194 offset:160
	s_waitcnt lgkmcnt(5)
	v_mfma_f32_32x32x16_bf16 v[220:235], v[156:159], v[136:139], v[220:235]
	ds_read_b128 v[248:251], v194 offset:6816
	s_waitcnt lgkmcnt(5)
	v_mfma_f32_32x32x16_bf16 v[204:219], v[160:163], v[140:143], v[204:219]
	ds_read_b128 v[152:155], v197
	s_waitcnt lgkmcnt(5)
	v_mfma_f32_32x32x16_bf16 v[220:235], v[164:167], v[140:143], v[220:235]
	ds_read_b128 v[156:159], v197 offset:4608
	s_waitcnt lgkmcnt(5)
	v_mfma_f32_32x32x16_bf16 v[204:219], v[236:239], v[144:147], v[204:219]
	ds_read_b128 v[160:163], v197 offset:32
	s_waitcnt lgkmcnt(5)
	v_mfma_f32_32x32x16_bf16 v[220:235], v[240:243], v[144:147], v[220:235]
	ds_read_b128 v[164:167], v197 offset:4640
	s_waitcnt lgkmcnt(5)
	v_mfma_f32_32x32x16_bf16 v[204:219], v[244:247], v[148:151], v[204:219]
	ds_read_b128 v[236:239], v197 offset:64
	s_waitcnt lgkmcnt(5)
	v_mfma_f32_32x32x16_bf16 v[220:235], v[248:251], v[148:151], v[220:235]
	ds_read_b128 v[240:243], v197 offset:4672
	s_nop 7
	v_max3_f32 v199, v204, v205, v206
	s_nop 1
	v_max3_f32 v252, v220, v221, v222
	v_max3_f32 v199, v199, v207, v208
	v_max3_f32 v252, v252, v223, v224
	v_max3_f32 v199, v199, v209, v210
	v_max3_f32 v252, v252, v225, v226
	v_max3_f32 v199, v199, v211, v212
	v_max3_f32 v252, v252, v227, v228
	v_max3_f32 v199, v199, v213, v214
	v_max3_f32 v252, v252, v229, v230
	v_max3_f32 v199, v199, v215, v216
	v_max3_f32 v252, v252, v231, v232
	v_max3_f32 v199, v199, v217, v218
	v_max3_f32 v252, v252, v233, v234
	v_max3_f32 v199, v199, v219, v235
	v_max_f32_e32 v199, v199, v252
	v_mov_b32_e32 v252, v199
	s_nop 1
	v_permlane32_swap_b32_e32 v199, v252
	v_max_f32_e32 v199, v199, v252
	v_cmp_lt_f32_e32 vcc, s51, v199
	s_cbranch_vccnz .Lmla_rare1b
; template <int DQK, int DV, int MODE, int QPRE, bool DIFF> ...
;     ...
;                 float ls = 0.f;
; #pragma unroll
;                 for (int r = 0; r < 16; ++r) { s0[r] = __builtin_amdgcn_exp2f(s0[r]); s1[r] = __builtin_amdgcn_exp2f(s1[r]); ls = fadd_s(ls, fadd_s(s0[r], s1[r])); }
;                 l_run += ls;
;             } else {
;                 const bool diag = (t == my_last);
;                 const int qrel = q0 + wid * 32 + l32 - t * 64;
;                 float kp[32], gprod[8];
; #pragma unroll
;                 for (int k = 0; k < 8; ++k) {
; #pragma unroll
;                     for (int e = 0; e < 4; ++e) {
;                         const int r = (k & 3) * 4 + e;
;                         const float z2 = __builtin_amdgcn_fmed3f((k < 4) ? s0[r] : s1[r], -126.0f, 126.0f);
;                         const float E = __builtin_amdgcn_exp2f(z2);
;                         const float keep = __builtin_amdgcn_rcpf(fadd_s(E, 1.0f)), beta = fmul_s(E, keep);
;                         kp[k * 4 + e] = keep;
;                         if (k < 4) s0[r] = beta; else s1[r] = beta;
;                     }
;                 }
;                 if (diag) {
;                     asm volatile("" ::: "memory");
; #pragma unroll
;                     for (int k = 0; k < 8; ++k)
; #pragma unroll
;                         for (int e = 0; e < 4; ++e) { const int r = (k & 3) * 4 + e; const int kl = (k >> 2) * 32 + e + 8 * (k & 3) + 4 * hi; const bool valid = kl < qrel;
;                             kp[k * 4 + e] = valid ? kp[k * 4 + e] : 1.0f; if (k < 4) s0[r] = valid ? s0[r] : 0.f; else s1[r] = valid ? s1[r] : 0.f; }
;                 }
; #pragma unroll
;                 for (int k = 0; k < 8; ++k) gprod[k] = fmul_s(fmul_s(kp[k * 4], kp[k * 4 + 1]), fmul_s(kp[k * 4 + 2], kp[k * 4 + 3]));
;                 float base[8]; float suf = 1.0f;
; #pragma unroll
;                 for (int k = 7; k >= 0; --k) { float glo, ghi; swap32(gprod[k], glo, ghi); base[k] = fmul_s(fmul_s(Rp, suf), (hi == 0 ? ghi : 1.0f)); suf = fmul_s(suf, fmul_s(glo, ghi)); }
;                 Rp *= suf;
;                 { const bool nd = __all(Rp == 0.0f); if (nd && !sb_done && lane == 0) __hip_atomic_fetch_add(sbcnt, 1u, __ATOMIC_RELAXED, __HIP_MEMORY_SCOPE_WORKGROUP); sb_done = nd; }
; #pragma unroll
;                 for (int k = 0; k < 8; ++k) {
.Lmla_back1b:
	v_exp_f32_e32 v204, v204
	v_exp_f32_e32 v205, v205
	v_exp_f32_e32 v206, v206
	v_exp_f32_e32 v207, v207
	v_exp_f32_e32 v208, v208
	v_exp_f32_e32 v209, v209
	v_exp_f32_e32 v210, v210
	v_exp_f32_e32 v211, v211
	v_add_f32_e32 v252, v204, v205
	v_add_f32_e32 v252, v252, v206
	v_add_f32_e32 v252, v252, v207
	v_add_f32_e32 v252, v252, v208
	v_add_f32_e32 v252, v252, v209
	v_add_f32_e32 v252, v252, v210
	v_add_f32_e32 v252, v252, v211
	v_cvt_pk_bf16_f32 v204, v204, v205
	v_cvt_pk_bf16_f32 v205, v206, v207
	v_cvt_pk_bf16_f32 v206, v208, v209
	v_cvt_pk_bf16_f32 v207, v210, v211
	v_exp_f32_e32 v212, v212
	v_exp_f32_e32 v213, v213
	v_exp_f32_e32 v214, v214
	v_exp_f32_e32 v215, v215
	v_exp_f32_e32 v216, v216
	v_exp_f32_e32 v217, v217
	v_exp_f32_e32 v218, v218
	v_exp_f32_e32 v219, v219
	v_add_f32_e32 v252, v252, v212
	v_add_f32_e32 v252, v252, v213
	v_add_f32_e32 v252, v252, v214
	v_add_f32_e32 v252, v252, v215
	v_add_f32_e32 v252, v252, v216
	v_add_f32_e32 v252, v252, v217
	v_add_f32_e32 v252, v252, v218
	v_add_f32_e32 v252, v252, v219
	v_cvt_pk_bf16_f32 v208, v212, v213
	v_cvt_pk_bf16_f32 v209, v214, v215
	v_cvt_pk_bf16_f32 v210, v216, v217
	v_cvt_pk_bf16_f32 v211, v218, v219
	v_exp_f32_e32 v220, v220
	v_exp_f32_e32 v221, v221
	v_exp_f32_e32 v222, v222
	v_exp_f32_e32 v223, v223
	v_exp_f32_e32 v224, v224
	v_exp_f32_e32 v225, v225
	v_exp_f32_e32 v226, v226
	v_exp_f32_e32 v227, v227
	v_add_f32_e32 v253, v220, v221
	v_add_f32_e32 v253, v253, v222
	v_add_f32_e32 v253, v253, v223
	v_add_f32_e32 v253, v253, v224
	v_add_f32_e32 v253, v253, v225
	v_add_f32_e32 v253, v253, v226
	v_add_f32_e32 v253, v253, v227
	v_cvt_pk_bf16_f32 v212, v220, v221
	v_cvt_pk_bf16_f32 v213, v222, v223
	v_cvt_pk_bf16_f32 v214, v224, v225
	v_cvt_pk_bf16_f32 v215, v226, v227
	v_exp_f32_e32 v228, v228
	v_exp_f32_e32 v229, v229
	v_exp_f32_e32 v230, v230
	v_exp_f32_e32 v231, v231
	v_exp_f32_e32 v232, v232
	v_exp_f32_e32 v233, v233
	v_exp_f32_e32 v234, v234
	v_exp_f32_e32 v235, v235
	v_add_f32_e32 v253, v253, v228
	v_add_f32_e32 v253, v253, v229
	v_add_f32_e32 v253, v253, v230
	v_add_f32_e32 v253, v253, v231
	v_add_f32_e32 v253, v253, v232
	v_add_f32_e32 v253, v253, v233
	v_add_f32_e32 v253, v253, v234
	v_add_f32_e32 v253, v253, v235
	v_cvt_pk_bf16_f32 v216, v228, v229
	v_cvt_pk_bf16_f32 v217, v230, v231
	v_cvt_pk_bf16_f32 v218, v232, v233
	v_cvt_pk_bf16_f32 v219, v234, v235
	v_add_f32_e32 v252, v252, v253
	v_add_f32_e32 v196, v196, v252
	s_waitcnt lgkmcnt(5)
	v_mfma_f32_32x32x16_bf16 v[16:31], v[152:155], v[204:207], v[16:31]
	ds_read_b128 v[244:247], v197 offset:96
	s_waitcnt lgkmcnt(5)
	v_mfma_f32_32x32x16_bf16 v[0:15], v[156:159], v[204:207], v[0:15]
	ds_read_b128 v[248:251], v197 offset:4704
	s_waitcnt lgkmcnt(5)
	v_mfma_f32_32x32x16_bf16 v[16:31], v[160:163], v[208:211], v[16:31]
	s_waitcnt lgkmcnt(4)
	v_mfma_f32_32x32x16_bf16 v[0:15], v[164:167], v[208:211], v[0:15]
	s_waitcnt lgkmcnt(3)
	v_mfma_f32_32x32x16_bf16 v[16:31], v[236:239], v[212:215], v[16:31]
	s_waitcnt lgkmcnt(2)
	v_mfma_f32_32x32x16_bf16 v[0:15], v[240:243], v[212:215], v[0:15]
	s_waitcnt lgkmcnt(1)
	v_mfma_f32_32x32x16_bf16 v[16:31], v[244:247], v[216:219], v[16:31]
	s_waitcnt lgkmcnt(0)
	v_mfma_f32_32x32x16_bf16 v[0:15], v[248:251], v[216:219], v[0:15]
	s_branch .LBB0_1701
